# same XCD-local re-deal for the two sample/memory GEMMs of P1
# speedup vs baseline: 1.0122x; 1.0007x over previous
.LBB0_317:
	s_abs_i32 s4, s3
	v_cvt_f32_u32_e32 v0, s4
	s_sub_i32 s8, 0, s4
	s_add_i32 s5, s3, s2
	s_abs_i32 s7, s5
	v_rcp_iflag_f32_e32 v1, v0
	s_ashr_i32 s6, s5, 31
	v_mov_b32_e32 v0, v204
	v_mul_f32_e32 v1, 0x4f7ffffe, v1
	v_cvt_u32_f32_e32 v1, v1
	v_readfirstlane_b32 s5, v0
	v_readfirstlane_b32 s9, v1
	s_mul_i32 s8, s8, s9
	s_mul_hi_u32 s8, s9, s8
	s_add_i32 s9, s9, s8
	s_mul_hi_u32 s8, s7, s9
	s_mul_i32 s8, s8, s4
	s_sub_i32 s7, s7, s8
	s_sub_i32 s8, s7, s4
	s_cmp_ge_u32 s7, s4
	s_cselect_b32 s7, s8, s7
	s_sub_i32 s8, s7, s4
	s_cmp_ge_u32 s7, s4
	s_cselect_b32 s4, s8, s7
	s_xor_b32 s4, s4, s6
	s_sub_i32 s18, s4, s6
	s_and_b32 s8, s18, 7
	s_lshl_b32 s8, s8, 5
	s_lshr_b32 s4, s18, 3
	s_or_b32 s8, s8, s4
	s_cmp_eq_u32 s3, 0x100
	s_cselect_b32 s18, s8, s18
	s_cmpk_lt_i32 s18, 0x100
	s_cselect_b64 s[6:7], -1, 0
	s_cmpk_gt_i32 s18, 0xff
	s_movk_i32 s4, 0x100
	s_cbranch_scc1 .LBB0_330
	s_ashr_i32 s12, s5, 6
	s_lshl_b32 s8, s12, 7
	s_ashr_i32 s9, s8, 31
	s_lshl_b64 s[8:9], s[8:9], 1
	s_add_u32 s10, s54, s8
	s_addc_u32 s11, s55, s9
	v_and_b32_e32 v4, 48, v0
	v_mov_b32_e32 v5, 0
	v_lshl_add_u64 v[2:3], s[10:11], 0, v[4:5]
	s_mov_b64 s[10:11], 0x5000000
	v_lshl_add_u64 v[6:7], v[2:3], 0, s[10:11]
	s_add_u32 s8, s33, s8
	v_ashrrev_i32_e32 v2, 6, v0
	v_lshrrev_b32_e32 v3, 31, v0
	s_addc_u32 s9, s46, s9
	v_add_u32_e32 v3, v2, v3
	v_lshl_add_u64 v[8:9], s[8:9], 0, v[4:5]
	v_lshlrev_b32_e32 v4, 3, v3
	v_and_b32_e32 v3, 0xffffffe, v3
	v_and_b32_e32 v1, 63, v0
	v_sub_u32_e32 v2, v2, v3
	v_lshrrev_b32_e32 v3, 2, v0
	s_lshl_b32 s8, s12, 12
	v_lshl_add_u32 v1, v1, 4, 0
	v_and_b32_e32 v10, 0xfffffc0, v0
	v_and_b32_e32 v3, 12, v3
	v_and_b32_e32 v18, 15, v0
	v_cmp_gt_i32_e64 s[4:5], s4, v0
	v_and_b32_e32 v19, -16, v4
	v_lshl_add_u32 v20, v0, 4, 0
	v_lshl_add_u32 v21, v10, 4, v1
	v_lshl_or_b32 v22, v2, 4, v3
	s_lshl_b32 s9, s18, 5
	s_lshl_b32 s19, s3, 5
	v_bfi_b32 v23, 15, v0, v4
	v_mov_b32_e32 v24, 0x358637bd
	s_mov_b32 s20, 0x800000
	v_add_u32_e32 v25, s8, v1
	s_movk_i32 s21, 0x200
	s_mov_b32 s8, 0x3e0293ee
	s_movk_i32 s22, 0x3fff
	s_movk_i32 s23, 0xffef
	s_movk_i32 s24, 0xe00f
	s_movk_i32 s25, 0x1ff0
	s_mov_b32 s26, s18
	s_branch .LBB0_320
